# q12 + latent queue pop of the own-XCD head issued at key-loop exit, consumed at the next pop
# speedup vs baseline: 1.0069x; 1.0046x over previous
.LBB0_1299:
	s_mov_b32 s2, s75
	v_readlane_b32 s0, v255, 8
	s_waitcnt vmcnt(12)
	v_mbcnt_lo_u32_b32 v3, -1, 0
	v_mbcnt_hi_u32_b32 v3, -1, v3
	s_mov_b64 s[4:5], s[58:59]
	s_load_dwordx2 s[14:15], s[4:5], 0xe0
	s_load_dwordx2 s[6:7], s[4:5], 0x98
	v_add_u32_e32 v107, s0, v3
	s_waitcnt vmcnt(11)
	v_bfe_i32 v6, v107, 27, 1
	v_lshlrev_b32_e32 v0, 4, v107
	v_lshrrev_b32_e32 v6, 22, v6
	v_add_u32_e32 v6, v0, v6
	v_and_b32_e32 v6, 0xfffffc00, v6
	v_sub_u32_e32 v6, v0, v6
	v_ashrrev_i32_e32 v2, 31, v107
	v_lshrrev_b32_e32 v7, 4, v6
	v_lshrrev_b32_e32 v2, 26, v2
	v_bitop3_b32 v6, v7, v6, 32 bitop3:0x6c
	s_waitcnt lgkmcnt(0)
	s_add_u32 s38, s14, 0x29c00000
	v_add_u32_e32 v2, v107, v2
	v_ashrrev_i32_e32 v8, 31, v6
	s_addc_u32 s39, s15, 0
	v_ashrrev_i32_e32 v2, 6, v2
	v_lshrrev_b32_e32 v8, 26, v8
	s_add_u32 s40, s14, 0x39a00000
	v_lshlrev_b32_e32 v7, 3, v2
	v_add_u32_e32 v8, v6, v8
	s_addc_u32 s41, s15, 0
	v_and_b32_e32 v7, -16, v7
	v_ashrrev_i32_e32 v9, 6, v8
	s_add_u32 s42, s14, 0x3aa00000
	v_add_u32_e32 v120, v9, v7
	v_and_b32_e32 v7, 0xc0, v8
	s_addc_u32 s43, s15, 0
	v_lshlrev_b32_e32 v2, 5, v2
	v_sub_u32_e32 v6, v6, v7
	v_mov_b32_e32 v9, 1
	s_add_u32 s52, s14, 0x3bc00000
	v_and_b32_e32 v2, 32, v2
	v_ashrrev_i16_sdwa v6, v9, sext(v6) dst_sel:DWORD dst_unused:UNUSED_PAD src0_sel:DWORD src1_sel:BYTE_0
	v_add_u32_e32 v0, 0x2000, v0
	s_addc_u32 s53, s15, 0
	v_add_u32_sdwa v121, v2, sext(v6) dst_sel:DWORD dst_unused:UNUSED_PAD src0_sel:DWORD src1_sel:WORD_0
	v_ashrrev_i32_e32 v2, 31, v0
	s_add_u32 s54, s14, 0x45800000
	v_lshrrev_b32_e32 v2, 22, v2
	s_addc_u32 s55, s15, 0
	s_lshl_b32 s4, s60, 7
	s_mov_b32 s5, s75
	v_add_u32_e32 v2, v0, v2
	s_lshl_b64 s[4:5], s[4:5], 2
	v_ashrrev_i32_e32 v2, 10, v2
	s_add_u32 s10, s6, s4
	v_mul_i32_i24_e32 v6, 0x400, v2
	s_addc_u32 s11, s7, s5
	s_lshl_b32 s6, s60, 6
	s_mov_b32 s7, s75
	v_sub_u32_e32 v0, v0, v6
	s_lshl_b64 s[6:7], s[6:7], 2
	v_lshrrev_b32_e32 v6, 4, v0
	s_add_u32 s0, s14, s6
	v_bitop3_b32 v0, v6, v0, 32 bitop3:0x6c
	s_addc_u32 s6, s15, s7
	v_ashrrev_i32_e32 v7, 31, v0
	s_add_u32 s16, s0, 0x10000
	v_lshrrev_b32_e32 v7, 26, v7
	s_addc_u32 s17, s6, 0
	s_add_i32 s56, s2, 0x23f40
	v_lshlrev_b32_e32 v6, 3, v2
	v_add_u32_e32 v7, v0, v7
	s_add_u32 s57, s14, 0x21800000
	v_and_b32_e32 v6, 0x7ffffff0, v6
	v_ashrrev_i32_e32 v8, 6, v7
	s_addc_u32 s58, s15, 0
	s_lshl_b64 s[12:13], s[74:75], 2
	v_add_u32_e32 v122, v8, v6
	v_and_b32_e32 v6, 0xc0, v7
	s_add_u32 s0, s14, s12
	v_lshlrev_b32_e32 v2, 5, v2
	v_sub_u32_e32 v0, v0, v6
	s_addc_u32 s8, s15, s13
	v_and_b32_e32 v2, 32, v2
	v_ashrrev_i16_sdwa v0, v9, sext(v0) dst_sel:DWORD dst_unused:UNUSED_PAD src0_sel:DWORD src1_sel:BYTE_0
	s_add_u32 s18, s0, 0x200000
	v_and_b32_e32 v4, 63, v3
	v_and_b32_e32 v109, 15, v3
	v_bfe_u32 v5, v3, 4, 2
	v_add_u32_sdwa v123, v2, sext(v0) dst_sel:DWORD dst_unused:UNUSED_PAD src0_sel:DWORD src1_sel:WORD_0
	v_and_b32_e32 v0, 48, v3
	v_lshlrev_b32_e32 v3, 2, v3
	s_addc_u32 s19, s8, 0
	v_and_b32_e32 v3, 32, v3
	v_lshlrev_b32_e32 v6, 6, v109
	v_cmp_gt_u32_e64 s[8:9], 16, v4
	v_lshlrev_b32_e32 v4, 2, v4
	v_lshlrev_b32_e32 v2, 3, v5
	v_or_b32_e32 v7, v6, v0
	v_bitop3_b32 v6, v6, v3, v0 bitop3:0x36
	v_xor_b32_e32 v125, 64, v4
	v_xor_b32_e32 v126, 0x80, v4
	v_lshlrev_b32_e32 v4, 11, v109
	v_readlane_b32 s20, v254, 19
	v_cmp_eq_u32_e64 s[6:7], 0, v107
	s_add_i32 s59, s2, 0x10000
	s_add_i32 s60, s2, 0x14000
	v_add_u32_e32 v124, s2, v6
	v_lshlrev_b32_e32 v106, 2, v5
	v_add_u32_e32 v108, s2, v0
	v_lshl_add_u64 v[110:111], s[10:11], 0, v[0:1]
	v_bitop3_b32 v127, v7, s1, v3 bitop3:0xde
	v_lshlrev_b32_e32 v128, 1, v4
	v_lshlrev_b32_e32 v112, 1, v2
	v_readlane_b32 s21, v254, 20
	s_mov_b32 s80, 0
	s_branch .LBB0_1301

.LBB0_1301:
	s_barrier
	s_and_saveexec_b64 s[10:11], s[6:7]
	s_cbranch_execz .LBB0_1311
	s_andn2_b64 vcc, exec, s[20:21]
	v_mov_b32_e32 v0, -1
	s_cbranch_vccnz .LBB0_1306
	s_getreg_b32 s22, hwreg(HW_REG_XCC_ID, 0, 4)
	s_and_b32 s22, s22, 7
	s_mov_b32 s23, 0
	s_cmp_eq_u32 s80, 0
	s_cbranch_scc1 .Lq_try
	s_mov_b32 s80, 0
	s_mov_b32 s22, s32
	s_mov_b32 s24, s32
	s_waitcnt vmcnt(0)
	v_readfirstlane_b32 s0, v220
	s_nop 3
	s_cmpk_lt_u32 s0, 0x78
	s_cbranch_scc1 .Lq_got
	s_mov_b32 s23, 1

.LBB0_1333:
	v_lshl_add_u32 v0, s72, 14, v124
	ds_read_b128 v[22:25], v0 offset:53248
	ds_read_b128 v[26:29], v0 offset:55296
	ds_read_b128 v[10:13], v0 offset:49152
	ds_read_b128 v[18:21], v0 offset:51200
	s_mov_b32 s49, s48
	s_mov_b32 s50, s48
	s_mov_b32 s51, s48
	s_and_b64 s[98:99], s[20:21], s[26:27]
	s_and_b64 s[98:99], s[98:99], s[6:7]
	s_and_saveexec_b64 s[94:95], s[98:99]
	s_cbranch_execz .Lpf_end
	s_getreg_b32 s32, hwreg(HW_REG_XCC_ID, 0, 4)
	s_and_b32 s32, s32, 7
	s_lshl_b32 s98, s32, 10
	s_add_i32 s98, s98, 0x2000
	v_mov_b32_e32 v221, s98
	v_mov_b32_e32 v220, 1
	global_atomic_add v220, v221, v220, s[16:17] sc0
	s_mov_b32 s80, 1
.Lpf_end:
	s_or_b64 exec, exec, s[94:95]
	s_cmp_lg_u64 s[28:29], 0
	s_waitcnt lgkmcnt(0)
	v_mfma_f32_16x16x32_bf16 v[22:25], v[22:25], v[14:17], v[42:45]
	s_nop 2
	ds_read_b128 v[42:45], v0 offset:61440
	v_mfma_f32_16x16x32_bf16 v[26:29], v[26:29], v[14:17], v[34:37]
	s_nop 2
	ds_read_b128 v[34:37], v0 offset:59392
	s_waitcnt lgkmcnt(0)
	v_mfma_f32_16x16x32_bf16 v[42:45], v[42:45], v[14:17], v[46:49]
	s_nop 2
	ds_read_b128 v[46:49], v0 offset:63488
	s_waitcnt lgkmcnt(0)
	v_mfma_f32_16x16x32_bf16 v[46:49], v[46:49], v[14:17], v[38:41]
	s_nop 2
	ds_read_b128 v[38:41], v0 offset:50176
	v_mfma_f32_16x16x32_bf16 v[10:13], v[10:13], v[14:17], v[30:33]
	s_waitcnt lgkmcnt(0)
	v_mfma_f32_16x16x32_bf16 v[10:13], v[38:41], v[6:9], v[10:13]
	ds_read_b128 v[38:41], v0 offset:52224
	ds_read_b128 v[30:33], v0 offset:57344
	v_mfma_f32_16x16x32_bf16 v[18:21], v[18:21], v[14:17], v[50:53]
	s_waitcnt lgkmcnt(0)
	v_mfma_f32_16x16x32_bf16 v[18:21], v[38:41], v[6:9], v[18:21]
	ds_read_b128 v[38:41], v0 offset:54272
	s_waitcnt lgkmcnt(0)
	v_mfma_f32_16x16x32_bf16 v[22:25], v[38:41], v[6:9], v[22:25]
	ds_read_b128 v[38:41], v0 offset:56320
	s_waitcnt lgkmcnt(0)
	v_mfma_f32_16x16x32_bf16 v[26:29], v[38:41], v[6:9], v[26:29]
	ds_read_b128 v[38:41], v0 offset:58368
	v_mfma_f32_16x16x32_bf16 v[30:33], v[30:33], v[14:17], v[58:61]
	s_waitcnt lgkmcnt(0)
	v_mfma_f32_16x16x32_bf16 v[30:33], v[38:41], v[6:9], v[30:33]
	ds_read_b128 v[38:41], v0 offset:60416
	v_mfma_f32_16x16x32_bf16 v[34:37], v[34:37], v[14:17], v[54:57]
	s_waitcnt lgkmcnt(0)
	v_mfma_f32_16x16x32_bf16 v[34:37], v[38:41], v[6:9], v[34:37]
	ds_read_b128 v[38:41], v0 offset:62464
	s_waitcnt lgkmcnt(0)
	v_mfma_f32_16x16x32_bf16 v[38:41], v[38:41], v[6:9], v[42:45]
	s_nop 2
	ds_read_b128 v[42:45], v0 offset:64512
	s_waitcnt lgkmcnt(0)
	v_mfma_f32_16x16x32_bf16 v[42:45], v[42:45], v[6:9], v[46:49]
	s_nop 2
	v_mov_b64_e32 v[46:47], s[48:49]
	v_mov_b64_e32 v[48:49], s[50:51]
	s_nop 1
	v_mfma_f32_16x16x32_bf16 v[2:5], v[46:49], v[14:17], v[2:5]
	v_mfma_f32_16x16x32_bf16 v[2:5], v[46:49], v[6:9], v[2:5]
	s_cbranch_scc0 .LBB0_1337
	s_nop 6
	v_or_b32_e32 v4, s30, v129
	v_ashrrev_i32_e32 v5, 31, v4
	v_lshlrev_b64 v[4:5], 9, v[4:5]
	v_lshl_add_u64 v[4:5], s[28:29], 0, v[4:5]
	v_lshlrev_b32_e32 v0, 2, v106
	v_lshl_add_u64 v[4:5], v[4:5], 0, v[0:1]
	global_store_dwordx4 v[4:5], v[10:13], off
	global_store_dwordx4 v[4:5], v[18:21], off offset:64
	global_store_dwordx4 v[4:5], v[22:25], off offset:128
	global_store_dwordx4 v[4:5], v[26:29], off offset:192
	global_store_dwordx4 v[4:5], v[30:33], off offset:256
	global_store_dwordx4 v[4:5], v[34:37], off offset:320
	global_store_dwordx4 v[4:5], v[38:41], off offset:384
	global_store_dwordx4 v[4:5], v[42:45], off offset:448
	s_and_saveexec_b64 s[34:35], s[8:9]
	v_readlane_b32 s72, v255, 9
	v_readlane_b32 s73, v255, 10
	s_cbranch_execz .LBB0_1336
	s_add_i32 s0, s30, s70
	s_add_i32 s30, s0, 0x4000
	v_or_b32_e32 v4, s30, v109
	v_ashrrev_i32_e32 v5, 31, v4
	v_lshl_add_u64 v[4:5], v[4:5], 2, s[28:29]
	s_addk_i32 s0, 0x4080
	global_store_dword v[4:5], v113, off
	v_or_b32_e32 v4, s0, v109
	v_ashrrev_i32_e32 v5, 31, v4
	v_lshl_add_u64 v[4:5], v[4:5], 2, s[28:29]
	global_store_dword v[4:5], v2, off
